# v5 + wave priority raised (s_setprio 2) while a workgroup runs its deferred conversion/copy loops next to its CU mate's GEMM
# speedup vs baseline: 1.0054x; 1.0054x over previous
; DEVI void convert_chunk_fp8(const float* __restrict__ src, unsigned char* __restrict__ dst, float scale, int tid) {
;   int o = tid * 16;
;   uint4 r;
;   unsigned rr[4];
; #pragma unroll
;   for (int q = 0; q < 4; ++q) {
;     float4 a = *reinterpret_cast<const float4*>(src + o + q * 4);
;     int p = __builtin_amdgcn_cvt_pk_fp8_f32(a.x * scale, a.y * scale, 0, false);
;     p = __builtin_amdgcn_cvt_pk_fp8_f32(a.z * scale, a.w * scale, p, true);
;     rr[q] = (unsigned)p;
;   }
;   r = make_uint4(rr[0], rr[1], rr[2], rr[3]);
;   *reinterpret_cast<uint4*>(dst + o) = r;
; }
; DEVI void phase_prep(const Params& P, int l, char* smem) {
;     ...
;     } else if (id < C1) {
;       int q = id - C0;
;       convert_chunk_fp8(P.in[26] + (long)l * 16777216 + (long)q * 4096, (unsigned char*)(ws + O_UTB) + (long)q * 4096, U_SCALE, tid);
;     } else if (id < C2) {
;       int q = id - C1;
;       convert_chunk_fp8(P.in[27] + (long)l * 16777216 + (long)q * 4096, (unsigned char*)(ws + O_VTB) + (long)q * 4096, V_SCALE, tid);
.LBB0_728:
	s_or_b64 exec, exec, s[26:27]
	s_barrier
	v_readlane_b32 s60, v252, 36
	s_cmp_lg_u32 s60, 0
	s_cbranch_scc1 .Ltb_skip_a
	v_readlane_b32 s60, v252, 32
	s_cmpk_lt_u32 s60, 0x100
	s_cbranch_scc0 .Ltb_skip_a
	s_setprio 2
	v_readlane_b32 s54, v253, 22
	v_readlane_b32 s55, v253, 23
	v_readlane_b32 s56, v253, 24
	v_readlane_b32 s57, v253, 25
	s_lshl_b32 s61, s0, 26
	s_add_u32 s54, s54, s61
	s_addc_u32 s55, s55, 0
	s_add_u32 s56, s56, s61
	s_addc_u32 s57, s57, 0
	v_lshlrev_b32_e32 v248, 6, v93
	v_lshlrev_b32_e32 v250, 4, v93
	v_mov_b32_e32 v251, 0
	v_lshl_add_u64 v[250:251], v[64:65], 0, v[250:251]

; DEVI char* wsp(const Params& P, size_t off) { asm volatile("" : "+s"(off)); return P.ws + off; }
; DEVI int ltid() { int t = threadIdx.x; asm volatile("" : "+v"(t)); return t; }
; #define ZERO_ACC(a) _Pragma("unroll") for (int m_ = 0; m_ < 4; ++m_) _Pragma("unroll") for (int n_ = 0; n_ < 4; ++n_) a[m_][n_] = f32x4{0.f, 0.f, 0.f, 0.f}
; DEVI void stage_tile(const bfu* __restrict__ g, int ld, int k0, char* lds, int tid) {
; #pragma unroll
;   for (int i = 0; i < 4; ++i) {
;     int b = tid * 16 + i * 4096;
;     int r = b >> 7, cp = (b >> 4) & 7, gc = cp ^ (r & 7);
;     __builtin_amdgcn_global_load_lds((const unsigned*)(g + (long)r * ld + k0 + gc * 8),
;                                      (unsigned*)(lds + b), 16, 0, 0);
;   }
; }
; DEVI void phase7(const Params& P, int l, int pass, char* smem) {
;   const int tid = ltid();
;   const int ntok = pass ? 8192 : 8448, base = pass ? 8448 : 0;
;   const int nM = ntok / 128, nN = 8;
;   const bfu* M = (const bfu*)wsp(P, O_CB);
;   const bfu* W = (const bfu*)wsp(P, O_WO);
;   float* pre = (float*)wsp(P, O_PRE);
;   for (int id = blockIdx.x; id < nM * nN; id += gridDim.x) {
;     int pm, pn; tile_rc_m(id, nM, nN, pm, pn);
;     f32x4 acc[4][4]; ZERO_ACC(acc);
;     gemm_core(acc, M + (long)pm * 128 * 1024, 1024, W + (long)pn * 128 * 1024, 1024, 1024, smem, tid);
;     epi_stage_f32(acc, smem, tid);
.Ltb_skip_a:
	s_setprio 0
	v_mov_b32_e32 v91, v93
	s_cmp_eq_u32 s90, 0
	s_movk_i32 s1, 0x210
	s_mov_b64 s[26:27], 0x8582000
	s_cselect_b32 s1, s1, 0x200
	s_mov_b64 s[26:27], 0x17d02000
	s_cmp_ge_i32 s74, s1
	s_cbranch_scc1 .LBB0_743
	v_ashrrev_i32_e32 v0, 3, v91
	v_lshlrev_b32_e32 v101, 4, v91
	v_xor_b32_e32 v4, v0, v91
	v_lshlrev_b32_e32 v4, 3, v4
	v_add_u32_e32 v103, 0x1000, v101
	v_and_b32_e32 v100, 56, v4
	v_ashrrev_i32_e32 v4, 7, v103
	v_xor_b32_e32 v8, v4, v91
	v_lshlrev_b32_e32 v8, 3, v8
	v_add_u32_e32 v105, 0x2000, v101
	v_and_b32_e32 v102, 56, v8
	v_ashrrev_i32_e32 v8, 7, v105
	v_xor_b32_e32 v12, v8, v91
	v_lshrrev_b32_e32 v16, 4, v91
	v_lshlrev_b32_e32 v12, 3, v12
	v_add_u32_e32 v107, 0x3000, v101
	v_and_b32_e32 v20, 7, v91
	v_and_b32_e32 v104, 56, v12
	v_ashrrev_i32_e32 v12, 7, v107
	v_bitop3_b32 v16, v16, v20, 3 bitop3:0x6c
	v_bfe_u32 v17, v91, 4, 2
	v_xor_b32_e32 v18, v12, v91
	v_lshlrev_b32_e32 v146, 4, v16
	v_lshlrev_b32_e32 v16, 7, v91
	v_lshlrev_b32_e32 v18, 3, v18
	v_and_b32_e32 v148, 0x2780, v16
	v_bitop3_b32 v16, v17, v20, 4 bitop3:0x36
	v_and_b32_e32 v106, 56, v18
	v_and_b32_e32 v18, 15, v91
	v_lshrrev_b32_e32 v19, 1, v91
	s_mov_b32 s2, 0x1ffffc0
	v_lshlrev_b32_e32 v149, 4, v16
	v_lshrrev_b32_e32 v16, 2, v91
	v_and_or_b32 v18, v19, s2, v18
	v_and_b32_e32 v16, 12, v16
	s_mov_b32 s2, 0x7fffc0
	v_and_or_b32 v16, v19, s2, v16
	v_and_b32_e32 v17, 0x4f, v91
	v_lshlrev_b32_e32 v16, 9, v16
	v_ashrrev_i32_e32 v1, 31, v0
	v_lshl_or_b32 v150, v17, 2, v16
	v_lshlrev_b32_e32 v16, 2, v91
	v_lshlrev_b64 v[2:3], 10, v[0:1]
	v_ashrrev_i32_e32 v5, 31, v4
	v_and_b32_e32 v151, 0x7c, v16
	v_lshlrev_b64 v[16:17], 11, v[0:1]
	v_bitop3_b32 v0, v0, 7, v91 bitop3:0x48
	v_lshlrev_b64 v[6:7], 10, v[4:5]
	v_lshl_or_b32 v16, v0, 4, v16
	v_readlane_b32 s4, v252, 25
	v_lshlrev_b64 v[0:1], 11, v[4:5]
	v_bitop3_b32 v4, v4, 7, v91 bitop3:0x48
	v_ashrrev_i32_e32 v9, 31, v8
	v_readlane_b32 s5, v252, 26
	v_lshl_or_b32 v0, v4, 4, v0
	v_bitop3_b32 v4, v8, 7, v91 bitop3:0x48
	v_lshl_add_u64 v[110:111], s[4:5], 0, v[0:1]
	v_lshlrev_b64 v[0:1], 11, v[8:9]
	v_ashrrev_i32_e32 v13, 31, v12
	v_lshl_or_b32 v0, v4, 4, v0
	v_lshl_add_u64 v[112:113], s[4:5], 0, v[0:1]
	v_lshlrev_b64 v[0:1], 11, v[12:13]
	v_bitop3_b32 v4, v12, 7, v91 bitop3:0x48
	v_lshlrev_b64 v[10:11], 10, v[8:9]
	v_lshlrev_b64 v[14:15], 10, v[12:13]
	v_lshl_or_b32 v0, v4, 4, v0
	v_lshlrev_b32_e32 v147, 7, v18
	v_lshlrev_b32_e32 v152, 2, v151
	v_lshl_add_u64 v[108:109], s[4:5], 0, v[16:17]
	v_lshl_add_u64 v[114:115], s[4:5], 0, v[0:1]
	v_lshlrev_b64 v[116:117], 1, v[2:3]
	v_lshlrev_b64 v[118:119], 1, v[6:7]
	v_lshlrev_b64 v[120:121], 1, v[10:11]
	v_lshlrev_b64 v[122:123], 1, v[14:15]
	s_mov_b32 s2, s74

; DEVI void convert_chunk_fp8(const float* __restrict__ src, unsigned char* __restrict__ dst, float scale, int tid) {
;   int o = tid * 16;
;   uint4 r;
;   unsigned rr[4];
; #pragma unroll
;   for (int q = 0; q < 4; ++q) {
;     float4 a = *reinterpret_cast<const float4*>(src + o + q * 4);
;     int p = __builtin_amdgcn_cvt_pk_fp8_f32(a.x * scale, a.y * scale, 0, false);
;     p = __builtin_amdgcn_cvt_pk_fp8_f32(a.z * scale, a.w * scale, p, true);
;     rr[q] = (unsigned)p;
;   }
;   r = make_uint4(rr[0], rr[1], rr[2], rr[3]);
;   *reinterpret_cast<uint4*>(dst + o) = r;
; }
; DEVI void phase_prep(const Params& P, int l, char* smem) {
;     ...
;     } else if (id < C1) {
;       int q = id - C0;
;       convert_chunk_fp8(P.in[26] + (long)l * 16777216 + (long)q * 4096, (unsigned char*)(ws + O_UTB) + (long)q * 4096, U_SCALE, tid);
;     } else if (id < C2) {
;       int q = id - C1;
;       convert_chunk_fp8(P.in[27] + (long)l * 16777216 + (long)q * 4096, (unsigned char*)(ws + O_VTB) + (long)q * 4096, V_SCALE, tid);
.LBB0_743:
	v_readlane_b32 s60, v252, 36
	s_cmp_lg_u32 s60, 0
	s_cbranch_scc1 .Ltb_skip_b
	v_readlane_b32 s60, v252, 32
	s_cmpk_lt_u32 s60, 0x100
	s_cbranch_scc1 .Ltb_skip_b
	s_setprio 2
	v_readlane_b32 s54, v253, 22
	v_readlane_b32 s55, v253, 23
	v_readlane_b32 s56, v253, 24
	v_readlane_b32 s57, v253, 25
	s_lshl_b32 s61, s0, 26
	s_add_u32 s54, s54, s61
	s_addc_u32 s55, s55, 0
	s_add_u32 s56, s56, s61
	s_addc_u32 s57, s57, 0
	v_lshlrev_b32_e32 v248, 6, v93
	v_lshlrev_b32_e32 v250, 4, v93
	v_mov_b32_e32 v251, 0
	v_lshl_add_u64 v[250:251], v[64:65], 0, v[250:251]

; DEVI unsigned xb_add(unsigned* p, unsigned v) { return __hip_atomic_fetch_add(p, v, __ATOMIC_RELAXED, __HIP_MEMORY_SCOPE_AGENT); }
; DEVI void xcd_barrier(unsigned* bar, unsigned x, unsigned nloc, unsigned nx) {
;   asm volatile("s_waitcnt vmcnt(0)" ::: "memory");
;   __syncthreads();
;   if (threadIdx.x == 0) {
;     __builtin_amdgcn_s_waitcnt(0);
;     const unsigned old = xb_add(&bar[XB_XSUB(x)], 1u);
;     const unsigned gen = old / nloc;
;     if (old + 1u == (gen + 1u) * nloc) {
;       __builtin_amdgcn_fence(__ATOMIC_RELEASE, "agent");
;       asm volatile("s_waitcnt vmcnt(0)" ::: "memory");
;       const unsigned og = xb_add(&bar[XB_TOP], 1u);
;       const unsigned tg = og / nx;
;       if (og + 1u == (tg + 1u) * nx) xb_add(&bar[XB_TOPGEN], 1u);
.Ltb_skip_b:
	s_setprio 0
	s_waitcnt vmcnt(0)
	s_barrier
	s_mov_b64 s[26:27], exec
	v_readlane_b32 s40, v253, 4
	v_readlane_b32 s41, v253, 5
	s_and_b64 s[40:41], s[26:27], s[40:41]
	s_mov_b64 exec, s[40:41]
	s_cbranch_execz .LBB0_780
	s_mov_b64 s[40:41], exec
	v_mbcnt_lo_u32_b32 v0, s40, 0
	v_mbcnt_hi_u32_b32 v0, s41, v0
	v_cmp_eq_u32_e32 vcc, 0, v0
	s_waitcnt vmcnt(0) expcnt(0) lgkmcnt(0)
	s_and_saveexec_b64 s[42:43], vcc
	s_cbranch_execz .LBB0_746
	s_bcnt1_i32_b64 s1, s[40:41]
	v_readlane_b32 s4, v253, 30
	v_mov_b32_e32 v1, s1
	v_readlane_b32 s5, v253, 31
	s_nop 4
	global_atomic_add v1, v89, v1, s[4:5] sc0
